# GEMM tile boundary: wave halves re-synchronised per tile so both epilogues run concurrently (was serial)
# speedup vs baseline: 1.0878x; 1.0072x over previous
; #define LAS __attribute__((address_space(3)))
; #define PG8_STAGE(bufoff, gbase, voff) do { _Pragma("unroll") for (int _i = 0; _i < 2; ++_i) \
;         __builtin_amdgcn_global_load_lds((const unsigned*)((const char*)(gbase) + (voff)[_i]), (LAS unsigned*)(lds + (bufoff) + ldsw + _i * 8192), 16, 0, 0); } while (0)
; #define PG8_LDA(dst, b, h) do { _Pragma("unroll") for (int m = 0; m < 4; ++m) _Pragma("unroll") for (int k = 0; k < 2; ++k) dst[m][k] = *(const LAS bf16x8*)(lds + PG8_SA(b, h) + aoff + m * 2048 + k * 1024); } while (0)
; #define PG8_LDB(dst, b, h) do { _Pragma("unroll") for (int n = 0; n < 2; ++n) _Pragma("unroll") for (int k = 0; k < 2; ++k) dst[n][k] = *(const LAS bf16x8*)(lds + PG8_SB(b, h) + boff + n * 2048 + k * 1024); } while (0)
; #define PG8_WAIT_L(n) asm volatile("s_waitcnt lgkmcnt(" #n ")" ::: "memory")
; #define PG8_BAR __builtin_amdgcn_s_barrier()
; template <class Epi>
; __device__ __forceinline__ void gemm_phase(LAS unsigned char* lds, const Gemm g, const StaticOrder& S, const Epi& E) {
;     ...
;     for (;;) {
;         const bool has_next = S.next(ui + 1, nxt);
;         const char* nA = has_next ? (const char*)g.A + (size_t)nxt.pm * tstepA : cA; const char* nB = has_next ? (const char*)g.Bt + (size_t)nxt.pn * tstepB : cB;
;         for (int t = 0; t < nt; t += 2) {
;             const bool last = (t == nt - 2);
;             const char* a1 = cA + (size_t)(t + 1) * kstep;
;             const char* a2 = last ? nA : cA + (size_t)(t + 2) * kstep; const char* b2 = last ? nB : cB + (size_t)(t + 2) * kstep;
;             const char* a3 = a2 + kstep; const char* b3 = b2 + kstep;
;             if (E.rowscale() && t == 0 && wid < 4) __builtin_amdgcn_global_load_lds((const unsigned*)(E.row_ptr() + cur.pm * 256 + tid), (LAS unsigned*)(rsl + (ui & 1) * 256 + wid * 64), 4, 0, 0);
;             PG8_LDB(B0, 0, 0); PG8_SCHED; PG8_LDA(At, 0, 0); PG8_STAGE(PG8_SA(1, 1), a1 + hstepA, voffA);
;             PG8_WAIT_L(8); PG8_BAR; PG8_WAIT_L(0); PG8_MMA(0, 0, At, B0); PG8_BAR; PG8_SCHED;
;     ...
;         if (!has_next) break;
; #pragma unroll
;         for (int a = 0; a < 2; ++a)
; #pragma unroll
;             for (int b = 0; b < 2; ++b)
; #pragma unroll
;                 for (int m = 0; m < 4; ++m)
; #pragma unroll
;                     for (int n = 0; n < 2; ++n) acc[a][b][m][n] = (f32x4){0.f, 0.f, 0.f, 0.f};
;         cur = nxt; cA = nA; cB = nB; ++ui;
;     }
.LBB0_115:
	s_lshl_b32 s34, s20, 8
	s_lshl_b32 s20, s68, 8
	s_and_b32 s20, s20, 0x100
	s_lshl_b32 s44, s20, 2
	s_ashr_i32 s35, s34, 31
	s_add_i32 s68, s18, s44
	s_add_u32 s36, s36, 0x80
	s_addc_u32 s37, s37, 0
	s_add_u32 s69, s70, 0x100
	v_mov_b32_e32 v0, 0
	s_addc_u32 s70, s71, 0
	s_mov_b32 s44, 0
	v_mov_b32_e32 v1, v0
	v_mov_b32_e32 v2, v0
	v_mov_b32_e32 v3, v0
	v_mov_b32_e32 v4, v0
	v_mov_b32_e32 v5, v0
	v_mov_b32_e32 v6, v0
	v_mov_b32_e32 v7, v0
	v_mov_b32_e32 v8, v0
	v_mov_b32_e32 v9, v0
	v_mov_b32_e32 v10, v0
	v_mov_b32_e32 v11, v0
	v_mov_b32_e32 v16, v0
	v_mov_b32_e32 v17, v0
	v_mov_b32_e32 v18, v0
	v_mov_b32_e32 v19, v0
	v_mov_b32_e32 v24, v0
	v_mov_b32_e32 v25, v0
	v_mov_b32_e32 v26, v0
	v_mov_b32_e32 v27, v0
	v_mov_b32_e32 v32, v0
	v_mov_b32_e32 v33, v0
	v_mov_b32_e32 v34, v0
	v_mov_b32_e32 v35, v0
	v_mov_b32_e32 v40, v0
	v_mov_b32_e32 v41, v0
	v_mov_b32_e32 v42, v0
	v_mov_b32_e32 v43, v0
	v_mov_b32_e32 v48, v0
	v_mov_b32_e32 v49, v0
	v_mov_b32_e32 v50, v0
	v_mov_b32_e32 v51, v0
	v_mov_b32_e32 v12, v0
	v_mov_b32_e32 v13, v0
	v_mov_b32_e32 v14, v0
	v_mov_b32_e32 v15, v0
	v_mov_b32_e32 v20, v0
	v_mov_b32_e32 v21, v0
	v_mov_b32_e32 v22, v0
	v_mov_b32_e32 v23, v0
	v_mov_b32_e32 v28, v0
	v_mov_b32_e32 v29, v0
	v_mov_b32_e32 v30, v0
	v_mov_b32_e32 v31, v0
	v_mov_b32_e32 v36, v0
	v_mov_b32_e32 v37, v0
	v_mov_b32_e32 v38, v0
	v_mov_b32_e32 v39, v0
	v_mov_b32_e32 v44, v0
	v_mov_b32_e32 v45, v0
	v_mov_b32_e32 v46, v0
	v_mov_b32_e32 v47, v0
	v_mov_b32_e32 v52, v0
	v_mov_b32_e32 v53, v0
	v_mov_b32_e32 v54, v0
	v_mov_b32_e32 v55, v0
	v_mov_b32_e32 v56, v0
	v_mov_b32_e32 v57, v0
	v_mov_b32_e32 v58, v0
	v_mov_b32_e32 v59, v0
	v_mov_b32_e32 v60, v0
	v_mov_b32_e32 v61, v0
	v_mov_b32_e32 v62, v0
	v_mov_b32_e32 v63, v0
	v_mov_b32_e32 v64, v0
	v_mov_b32_e32 v65, v0
	v_mov_b32_e32 v66, v0
	v_mov_b32_e32 v67, v0
	v_mov_b32_e32 v68, v0
	v_mov_b32_e32 v69, v0
	v_mov_b32_e32 v70, v0
	v_mov_b32_e32 v71, v0
	v_mov_b32_e32 v76, v0
	v_mov_b32_e32 v77, v0
	v_mov_b32_e32 v78, v0
	v_mov_b32_e32 v79, v0
	v_mov_b32_e32 v84, v0
	v_mov_b32_e32 v85, v0
	v_mov_b32_e32 v86, v0
	v_mov_b32_e32 v87, v0
	v_mov_b32_e32 v92, v0
	v_mov_b32_e32 v93, v0
	v_mov_b32_e32 v94, v0
	v_mov_b32_e32 v95, v0
	v_mov_b32_e32 v100, v0
	v_mov_b32_e32 v101, v0
	v_mov_b32_e32 v102, v0
	v_mov_b32_e32 v103, v0
	v_mov_b32_e32 v108, v0
	v_mov_b32_e32 v109, v0
	v_mov_b32_e32 v110, v0
	v_mov_b32_e32 v111, v0
	v_mov_b32_e32 v116, v0
	v_mov_b32_e32 v117, v0
	v_mov_b32_e32 v118, v0
	v_mov_b32_e32 v119, v0
	v_mov_b32_e32 v72, v0
	v_mov_b32_e32 v73, v0
	v_mov_b32_e32 v74, v0
	v_mov_b32_e32 v75, v0
	v_mov_b32_e32 v80, v0
	v_mov_b32_e32 v81, v0
	v_mov_b32_e32 v82, v0
	v_mov_b32_e32 v83, v0
	v_mov_b32_e32 v88, v0
	v_mov_b32_e32 v89, v0
	v_mov_b32_e32 v90, v0
	v_mov_b32_e32 v91, v0
	v_mov_b32_e32 v96, v0
	v_mov_b32_e32 v97, v0
	v_mov_b32_e32 v98, v0
	v_mov_b32_e32 v99, v0
	v_mov_b32_e32 v104, v0
	v_mov_b32_e32 v105, v0
	v_mov_b32_e32 v106, v0
	v_mov_b32_e32 v107, v0
	v_mov_b32_e32 v112, v0
	v_mov_b32_e32 v113, v0
	v_mov_b32_e32 v114, v0
	v_mov_b32_e32 v115, v0
	v_mov_b32_e32 v120, v0
	v_mov_b32_e32 v121, v0
	v_mov_b32_e32 v122, v0
	v_mov_b32_e32 v123, v0
	v_mov_b32_e32 v124, v0
	v_mov_b32_e32 v125, v0
	v_mov_b32_e32 v126, v0
	v_mov_b32_e32 v127, v0
	s_waitcnt lgkmcnt(0)
	v_lshl_add_u64 v[128:129], s[34:35], 2, v[180:181]
	s_cmp_lt_u32 s75, 2
	s_cbranch_scc1 .Lresync_y
	s_cmpk_lt_u32 s79, 0x100
	s_cbranch_scc1 .Lresync_y
	s_barrier
.Lresync_y:
	s_branch .LBB0_117
.LBB0_116:
	s_add_i32 s35, s44, 2
	s_add_u32 s46, s36, 0x80
	s_addc_u32 s45, s37, 0
	s_cmp_eq_u32 s17, s44
	s_cselect_b32 s45, s29, s45
	s_cselect_b32 s44, s28, s46
	s_cselect_b32 s47, s31, s70
	s_cselect_b32 s46, s30, s69
	s_add_i32 s71, 0, 0x10000
	v_add_u32_e32 v142, s71, v225
	ds_read_b128 v[130:133], v142
	ds_read_b128 v[134:137], v142 offset:1024
	ds_read_b128 v[138:141], v142 offset:2048
	ds_read_b128 v[142:145], v142 offset:3072
	v_lshl_add_u64 v[166:167], s[36:37], 0, v[186:187]
	s_add_i32 m0, s39, 0xc000
	ds_read_b128 v[146:149], v228
	ds_read_b128 v[150:153], v228 offset:1024
	ds_read_b128 v[154:157], v228 offset:2048
	ds_read_b128 v[158:161], v228 offset:3072
	ds_read_b128 v[162:165], v228 offset:4096
	ds_read_b128 v[190:193], v228 offset:5120
	ds_read_b128 v[194:197], v228 offset:6144
	ds_read_b128 v[198:201], v228 offset:7168
	global_load_lds_dwordx4 v[166:167], off
	v_lshl_add_u64 v[166:167], s[36:37], 0, v[188:189]
	s_add_i32 m0, s39, 0xe000
	s_nop 0
	global_load_lds_dwordx4 v[166:167], off
	s_waitcnt lgkmcnt(8)
	s_barrier
	s_waitcnt lgkmcnt(0)
	s_waitcnt lgkmcnt(0)
	v_mfma_f32_16x16x32_bf16 v[124:127], v[130:133], v[146:149], v[124:127]
	v_mfma_f32_16x16x32_bf16 v[120:123], v[138:141], v[146:149], v[120:123]
	v_mfma_f32_16x16x32_bf16 v[112:115], v[130:133], v[154:157], v[112:115]
	v_mfma_f32_16x16x32_bf16 v[104:107], v[138:141], v[154:157], v[104:107]
	v_mfma_f32_16x16x32_bf16 v[96:99], v[130:133], v[162:165], v[96:99]
	v_mfma_f32_16x16x32_bf16 v[88:91], v[138:141], v[162:165], v[88:91]
	v_mfma_f32_16x16x32_bf16 v[80:83], v[130:133], v[194:197], v[80:83]
	v_mfma_f32_16x16x32_bf16 v[72:75], v[138:141], v[194:197], v[72:75]
	v_mfma_f32_16x16x32_bf16 v[124:127], v[134:137], v[150:153], v[124:127]
	v_mfma_f32_16x16x32_bf16 v[120:123], v[142:145], v[150:153], v[120:123]
	v_mfma_f32_16x16x32_bf16 v[112:115], v[134:137], v[158:161], v[112:115]
	v_mfma_f32_16x16x32_bf16 v[104:107], v[142:145], v[158:161], v[104:107]
	v_mfma_f32_16x16x32_bf16 v[96:99], v[134:137], v[190:193], v[96:99]
	v_mfma_f32_16x16x32_bf16 v[88:91], v[142:145], v[190:193], v[88:91]
	v_mfma_f32_16x16x32_bf16 v[80:83], v[134:137], v[198:201], v[80:83]
	v_mfma_f32_16x16x32_bf16 v[72:75], v[142:145], v[198:201], v[72:75]
	s_barrier
; #define PG8_STAGE(bufoff, gbase, voff) do { _Pragma("unroll") for (int _i = 0; _i < 2; ++_i) \
;         __builtin_amdgcn_global_load_lds((const unsigned*)((const char*)(gbase) + (voff)[_i]), (LAS unsigned*)(lds + (bufoff) + ldsw + _i * 8192), 16, 0, 0); } while (0)
; #define PG8_LDA(dst, b, h) do { _Pragma("unroll") for (int m = 0; m < 4; ++m) _Pragma("unroll") for (int k = 0; k < 2; ++k) dst[m][k] = *(const LAS bf16x8*)(lds + PG8_SA(b, h) + aoff + m * 2048 + k * 1024); } while (0)
; #define PG8_LDB(dst, b, h) do { _Pragma("unroll") for (int n = 0; n < 2; ++n) _Pragma("unroll") for (int k = 0; k < 2; ++k) dst[n][k] = *(const LAS bf16x8*)(lds + PG8_SB(b, h) + boff + n * 2048 + k * 1024); } while (0)
; #define PG8_MMA(ai, bj, At, Bt) do { __builtin_amdgcn_s_setprio(1); _Pragma("unroll") for (int m = 0; m < 4; ++m) _Pragma("unroll") for (int n = 0; n < 2; ++n) _Pragma("unroll") for (int k = 0; k < 2; ++k) \
;         acc[ai][bj][m][n] = __builtin_amdgcn_mfma_f32_16x16x32_bf16(Bt[n][k], At[m][k], acc[ai][bj][m][n], 0, 0, 0); __builtin_amdgcn_s_setprio(0); } while (0)
; #define PG8_WAIT_V(n) asm volatile("s_waitcnt vmcnt(" #n ")" ::: "memory")
; #define PG8_WAIT_L(n) asm volatile("s_waitcnt lgkmcnt(" #n ")" ::: "memory")
; #define PG8_BAR __builtin_amdgcn_s_barrier()
; #define PG8_SCHED __builtin_amdgcn_sched_barrier(0)
; template <class Epi>
; __device__ __forceinline__ void gemm_phase(LAS unsigned char* lds, const Gemm g, const StaticOrder& S, const Epi& E) {
;     ...
;             PG8_LDB(B1, 0, 1); PG8_STAGE(PG8_SB(0, 0), b2, voffB);
;             PG8_BAR; PG8_WAIT_L(0); PG8_MMA(0, 1, At, B1); PG8_BAR;
;             PG8_LDA(At, 0, 1); PG8_STAGE(PG8_SA(0, 0), a2, voffA);
;             PG8_BAR; PG8_WAIT_L(0); PG8_MMA(1, 0, At, B0); PG8_BAR; PG8_SCHED;
;             PG8_STAGE(PG8_SB(0, 1), b2 + hstepB, voffB);
;             PG8_WAIT_V(6); PG8_BAR; PG8_MMA(1, 1, At, B1); PG8_BAR;
;             PG8_LDB(B0, 1, 0); PG8_SCHED; PG8_LDA(At, 1, 0); PG8_STAGE(PG8_SA(0, 1), a2 + hstepA, voffA);
;             PG8_WAIT_L(8); PG8_BAR; PG8_WAIT_L(0); PG8_MMA(0, 0, At, B0); PG8_BAR; PG8_SCHED;
	s_add_i32 s72, 0, 0x14000
	v_add_u32_e32 v166, s72, v225
	s_add_i32 s71, s71, s57
	ds_read_b128 v[202:205], v166
	ds_read_b128 v[230:233], v166 offset:1024
	ds_read_b128 v[234:237], v166 offset:2048
	ds_read_b128 v[238:241], v166 offset:3072
	v_lshl_add_u64 v[166:167], s[46:47], 0, v[168:169]
	s_mov_b32 m0, s71
	v_lshl_add_u64 v[206:207], s[46:47], 0, v[178:179]
	global_load_lds_dwordx4 v[166:167], off
	s_add_i32 m0, s71, 0x2000
	s_nop 0
	global_load_lds_dwordx4 v[206:207], off
	s_barrier
	s_waitcnt lgkmcnt(0)
	s_waitcnt lgkmcnt(0)
	v_mfma_f32_16x16x32_bf16 v[116:119], v[202:205], v[146:149], v[116:119]
	v_mfma_f32_16x16x32_bf16 v[108:111], v[234:237], v[146:149], v[108:111]
	v_mfma_f32_16x16x32_bf16 v[100:103], v[202:205], v[154:157], v[100:103]
	v_mfma_f32_16x16x32_bf16 v[92:95], v[234:237], v[154:157], v[92:95]
	v_mfma_f32_16x16x32_bf16 v[84:87], v[202:205], v[162:165], v[84:87]
	v_mfma_f32_16x16x32_bf16 v[76:79], v[234:237], v[162:165], v[76:79]
	v_mfma_f32_16x16x32_bf16 v[68:71], v[202:205], v[194:197], v[68:71]
	v_mfma_f32_16x16x32_bf16 v[64:67], v[234:237], v[194:197], v[64:67]
	v_mfma_f32_16x16x32_bf16 v[116:119], v[230:233], v[150:153], v[116:119]
	v_mfma_f32_16x16x32_bf16 v[108:111], v[238:241], v[150:153], v[108:111]
	v_mfma_f32_16x16x32_bf16 v[100:103], v[230:233], v[158:161], v[100:103]
	v_mfma_f32_16x16x32_bf16 v[92:95], v[238:241], v[158:161], v[92:95]
	v_mfma_f32_16x16x32_bf16 v[84:87], v[230:233], v[190:193], v[84:87]
	v_mfma_f32_16x16x32_bf16 v[76:79], v[238:241], v[190:193], v[76:79]
	v_mfma_f32_16x16x32_bf16 v[68:71], v[230:233], v[198:201], v[68:71]
	v_mfma_f32_16x16x32_bf16 v[64:67], v[238:241], v[198:201], v[64:67]
	s_mov_b32 m0, s39
	v_lshl_add_u64 v[242:243], s[44:45], 0, v[174:175]
	s_barrier
	ds_read_b128 v[146:149], v228 offset:16384
	ds_read_b128 v[150:153], v228 offset:17408
	ds_read_b128 v[154:157], v228 offset:18432
	ds_read_b128 v[158:161], v228 offset:19456
	ds_read_b128 v[162:165], v228 offset:20480
	ds_read_b128 v[190:193], v228 offset:21504
	ds_read_b128 v[194:197], v228 offset:22528
	ds_read_b128 v[198:201], v228 offset:23552
	global_load_lds_dwordx4 v[242:243], off
	v_lshl_add_u64 v[244:245], s[44:45], 0, v[176:177]
	s_mov_b32 m0, s54
	s_nop 0
	global_load_lds_dwordx4 v[244:245], off
	s_barrier
	s_waitcnt lgkmcnt(0)
	s_waitcnt lgkmcnt(0)
	v_mfma_f32_16x16x32_bf16 v[60:63], v[130:133], v[146:149], v[60:63]
	v_mfma_f32_16x16x32_bf16 v[56:59], v[138:141], v[146:149], v[56:59]
	v_mfma_f32_16x16x32_bf16 v[52:55], v[130:133], v[154:157], v[52:55]
	v_mfma_f32_16x16x32_bf16 v[44:47], v[138:141], v[154:157], v[44:47]
	v_mfma_f32_16x16x32_bf16 v[36:39], v[130:133], v[162:165], v[36:39]
	v_mfma_f32_16x16x32_bf16 v[28:31], v[138:141], v[162:165], v[28:31]
	v_mfma_f32_16x16x32_bf16 v[20:23], v[130:133], v[194:197], v[20:23]
	v_mfma_f32_16x16x32_bf16 v[12:15], v[138:141], v[194:197], v[12:15]
	v_mfma_f32_16x16x32_bf16 v[60:63], v[134:137], v[150:153], v[60:63]
	v_mfma_f32_16x16x32_bf16 v[56:59], v[142:145], v[150:153], v[56:59]
	v_mfma_f32_16x16x32_bf16 v[52:55], v[134:137], v[158:161], v[52:55]
	v_mfma_f32_16x16x32_bf16 v[44:47], v[142:145], v[158:161], v[44:47]
	v_mfma_f32_16x16x32_bf16 v[36:39], v[134:137], v[190:193], v[36:39]
	v_mfma_f32_16x16x32_bf16 v[28:31], v[142:145], v[190:193], v[28:31]
	v_mfma_f32_16x16x32_bf16 v[20:23], v[134:137], v[198:201], v[20:23]
	v_mfma_f32_16x16x32_bf16 v[12:15], v[142:145], v[198:201], v[12:15]
	s_barrier
	s_add_u32 s46, s46, s50
	s_addc_u32 s47, s47, 0
	s_add_i32 s71, s72, s57
	v_lshl_add_u64 v[246:247], s[46:47], 0, v[168:169]
	s_mov_b32 m0, s71
	v_lshl_add_u64 v[248:249], s[46:47], 0, v[178:179]
	global_load_lds_dwordx4 v[246:247], off
	s_add_i32 m0, s71, 0x2000
	s_nop 0
	global_load_lds_dwordx4 v[248:249], off
	s_waitcnt vmcnt(6)
	s_barrier
	v_mfma_f32_16x16x32_bf16 v[48:51], v[202:205], v[146:149], v[48:51]
	v_mfma_f32_16x16x32_bf16 v[40:43], v[234:237], v[146:149], v[40:43]
	v_mfma_f32_16x16x32_bf16 v[32:35], v[202:205], v[154:157], v[32:35]
	v_mfma_f32_16x16x32_bf16 v[24:27], v[234:237], v[154:157], v[24:27]
	v_mfma_f32_16x16x32_bf16 v[16:19], v[202:205], v[162:165], v[16:19]
	v_mfma_f32_16x16x32_bf16 v[8:11], v[234:237], v[162:165], v[8:11]
	v_mfma_f32_16x16x32_bf16 v[4:7], v[202:205], v[194:197], v[4:7]
	v_mfma_f32_16x16x32_bf16 v[0:3], v[234:237], v[194:197], v[0:3]
	v_mfma_f32_16x16x32_bf16 v[48:51], v[230:233], v[150:153], v[48:51]
	v_mfma_f32_16x16x32_bf16 v[40:43], v[238:241], v[150:153], v[40:43]
	v_mfma_f32_16x16x32_bf16 v[32:35], v[230:233], v[158:161], v[32:35]
	v_mfma_f32_16x16x32_bf16 v[24:27], v[238:241], v[158:161], v[24:27]
	v_mfma_f32_16x16x32_bf16 v[16:19], v[230:233], v[190:193], v[16:19]
	v_mfma_f32_16x16x32_bf16 v[8:11], v[238:241], v[190:193], v[8:11]
	v_mfma_f32_16x16x32_bf16 v[4:7], v[230:233], v[198:201], v[4:7]
	v_mfma_f32_16x16x32_bf16 v[0:3], v[238:241], v[198:201], v[0:3]
	s_add_i32 s46, 0, 0x18000
	v_add_u32_e32 v142, s46, v225
	s_barrier
	ds_read_b128 v[130:133], v142
	ds_read_b128 v[134:137], v142 offset:1024
	ds_read_b128 v[138:141], v142 offset:2048
	ds_read_b128 v[142:145], v142 offset:3072
	s_add_u32 s44, s44, s74
	s_addc_u32 s45, s45, 0
	s_mov_b32 m0, s55
	v_lshl_add_u64 v[202:203], s[44:45], 0, v[174:175]
	ds_read_b128 v[146:149], v228 offset:32768
	ds_read_b128 v[150:153], v228 offset:33792
	ds_read_b128 v[154:157], v228 offset:34816
	ds_read_b128 v[158:161], v228 offset:35840
	ds_read_b128 v[162:165], v228 offset:36864
	ds_read_b128 v[190:193], v228 offset:37888
	ds_read_b128 v[194:197], v228 offset:38912
	ds_read_b128 v[198:201], v228 offset:39936
	global_load_lds_dwordx4 v[202:203], off
	v_lshl_add_u64 v[202:203], s[44:45], 0, v[176:177]
	s_mov_b32 m0, s3
	s_nop 0
	global_load_lds_dwordx4 v[202:203], off
	s_waitcnt lgkmcnt(8)
	s_barrier
; #define PG8_STAGE(bufoff, gbase, voff) do { _Pragma("unroll") for (int _i = 0; _i < 2; ++_i) \
;         __builtin_amdgcn_global_load_lds((const unsigned*)((const char*)(gbase) + (voff)[_i]), (LAS unsigned*)(lds + (bufoff) + ldsw + _i * 8192), 16, 0, 0); } while (0)
; #define PG8_LDA(dst, b, h) do { _Pragma("unroll") for (int m = 0; m < 4; ++m) _Pragma("unroll") for (int k = 0; k < 2; ++k) dst[m][k] = *(const LAS bf16x8*)(lds + PG8_SA(b, h) + aoff + m * 2048 + k * 1024); } while (0)
; #define PG8_LDB(dst, b, h) do { _Pragma("unroll") for (int n = 0; n < 2; ++n) _Pragma("unroll") for (int k = 0; k < 2; ++k) dst[n][k] = *(const LAS bf16x8*)(lds + PG8_SB(b, h) + boff + n * 2048 + k * 1024); } while (0)
; #define PG8_MMA(ai, bj, At, Bt) do { __builtin_amdgcn_s_setprio(1); _Pragma("unroll") for (int m = 0; m < 4; ++m) _Pragma("unroll") for (int n = 0; n < 2; ++n) _Pragma("unroll") for (int k = 0; k < 2; ++k) \
;         acc[ai][bj][m][n] = __builtin_amdgcn_mfma_f32_16x16x32_bf16(Bt[n][k], At[m][k], acc[ai][bj][m][n], 0, 0, 0); __builtin_amdgcn_s_setprio(0); } while (0)
; #define PG8_WAIT_V(n) asm volatile("s_waitcnt vmcnt(" #n ")" ::: "memory")
; #define PG8_WAIT_L(n) asm volatile("s_waitcnt lgkmcnt(" #n ")" ::: "memory")
; #define PG8_BAR __builtin_amdgcn_s_barrier()
; #define PG8_SCHED __builtin_amdgcn_sched_barrier(0)
; template <class Epi>
; __device__ __forceinline__ void gemm_phase(LAS unsigned char* lds, const Gemm g, const StaticOrder& S, const Epi& E) {
;     ...
;             PG8_WAIT_L(8); PG8_BAR; PG8_WAIT_L(0); PG8_MMA(0, 0, At, B0); PG8_BAR; PG8_SCHED;
;             PG8_LDB(B1, 1, 1); PG8_STAGE(PG8_SB(1, 0), b3, voffB);
;             PG8_BAR; PG8_WAIT_L(0); PG8_MMA(0, 1, At, B1); PG8_BAR;
;             PG8_LDA(At, 1, 1); PG8_STAGE(PG8_SA(1, 0), a3, voffA);
;             PG8_BAR; PG8_WAIT_L(0); PG8_MMA(1, 0, At, B0); PG8_BAR; PG8_SCHED;
;             PG8_STAGE(PG8_SB(1, 1), b3 + hstepB, voffB);
;             PG8_WAIT_V(6); PG8_BAR; PG8_MMA(1, 1, At, B1); PG8_BAR;
;         }
	s_waitcnt lgkmcnt(0)
	s_waitcnt lgkmcnt(0)
	v_mfma_f32_16x16x32_bf16 v[124:127], v[130:133], v[146:149], v[124:127]
	v_mfma_f32_16x16x32_bf16 v[120:123], v[138:141], v[146:149], v[120:123]
	v_mfma_f32_16x16x32_bf16 v[112:115], v[130:133], v[154:157], v[112:115]
	v_mfma_f32_16x16x32_bf16 v[104:107], v[138:141], v[154:157], v[104:107]
	v_mfma_f32_16x16x32_bf16 v[96:99], v[130:133], v[162:165], v[96:99]
	v_mfma_f32_16x16x32_bf16 v[88:91], v[138:141], v[162:165], v[88:91]
	v_mfma_f32_16x16x32_bf16 v[80:83], v[130:133], v[194:197], v[80:83]
	v_mfma_f32_16x16x32_bf16 v[72:75], v[138:141], v[194:197], v[72:75]
	v_mfma_f32_16x16x32_bf16 v[124:127], v[134:137], v[150:153], v[124:127]
	v_mfma_f32_16x16x32_bf16 v[120:123], v[142:145], v[150:153], v[120:123]
	v_mfma_f32_16x16x32_bf16 v[112:115], v[134:137], v[158:161], v[112:115]
	v_mfma_f32_16x16x32_bf16 v[104:107], v[142:145], v[158:161], v[104:107]
	v_mfma_f32_16x16x32_bf16 v[96:99], v[134:137], v[190:193], v[96:99]
	v_mfma_f32_16x16x32_bf16 v[88:91], v[142:145], v[190:193], v[88:91]
	v_mfma_f32_16x16x32_bf16 v[80:83], v[134:137], v[198:201], v[80:83]
	v_mfma_f32_16x16x32_bf16 v[72:75], v[142:145], v[198:201], v[72:75]
	s_barrier
	s_add_i32 s44, s46, s57
	v_add_u32_e32 v172, s78, v225
	v_lshl_add_u64 v[166:167], v[166:167], 0, s[88:89]
	s_mov_b32 m0, s44
	ds_read_b128 v[202:205], v172
	ds_read_b128 v[230:233], v172 offset:1024
	ds_read_b128 v[234:237], v172 offset:2048
	ds_read_b128 v[238:241], v172 offset:3072
	global_load_lds_dwordx4 v[166:167], off
	v_lshl_add_u64 v[166:167], v[206:207], 0, s[88:89]
	s_add_i32 m0, s44, 0x2000
	s_nop 0
	global_load_lds_dwordx4 v[166:167], off
	s_barrier
	s_waitcnt lgkmcnt(0)
	s_waitcnt lgkmcnt(0)
	v_mfma_f32_16x16x32_bf16 v[116:119], v[202:205], v[146:149], v[116:119]
	v_mfma_f32_16x16x32_bf16 v[108:111], v[234:237], v[146:149], v[108:111]
	v_mfma_f32_16x16x32_bf16 v[100:103], v[202:205], v[154:157], v[100:103]
	v_mfma_f32_16x16x32_bf16 v[92:95], v[234:237], v[154:157], v[92:95]
	v_mfma_f32_16x16x32_bf16 v[84:87], v[202:205], v[162:165], v[84:87]
	v_mfma_f32_16x16x32_bf16 v[76:79], v[234:237], v[162:165], v[76:79]
	v_mfma_f32_16x16x32_bf16 v[68:71], v[202:205], v[194:197], v[68:71]
	v_mfma_f32_16x16x32_bf16 v[64:67], v[234:237], v[194:197], v[64:67]
	v_mfma_f32_16x16x32_bf16 v[116:119], v[230:233], v[150:153], v[116:119]
	v_mfma_f32_16x16x32_bf16 v[108:111], v[238:241], v[150:153], v[108:111]
	v_mfma_f32_16x16x32_bf16 v[100:103], v[230:233], v[158:161], v[100:103]
	v_mfma_f32_16x16x32_bf16 v[92:95], v[238:241], v[158:161], v[92:95]
	v_mfma_f32_16x16x32_bf16 v[84:87], v[230:233], v[190:193], v[84:87]
	v_mfma_f32_16x16x32_bf16 v[76:79], v[238:241], v[190:193], v[76:79]
	v_mfma_f32_16x16x32_bf16 v[68:71], v[230:233], v[198:201], v[68:71]
	v_mfma_f32_16x16x32_bf16 v[64:67], v[238:241], v[198:201], v[64:67]
	s_mov_b32 m0, s60
	v_lshl_add_u64 v[166:167], v[242:243], 0, s[88:89]
	s_barrier
	ds_read_b128 v[146:149], v228 offset:49152
	ds_read_b128 v[150:153], v228 offset:50176
	ds_read_b128 v[154:157], v228 offset:51200
	ds_read_b128 v[158:161], v228 offset:52224
	ds_read_b128 v[162:165], v228 offset:53248
	ds_read_b128 v[190:193], v228 offset:54272
	ds_read_b128 v[194:197], v228 offset:55296
	ds_read_b128 v[198:201], v228 offset:56320
	global_load_lds_dwordx4 v[166:167], off
	v_lshl_add_u64 v[166:167], v[244:245], 0, s[88:89]
	s_mov_b32 m0, s61
	s_nop 0
	global_load_lds_dwordx4 v[166:167], off
	s_barrier
	s_waitcnt lgkmcnt(0)
	s_waitcnt lgkmcnt(0)
	v_mfma_f32_16x16x32_bf16 v[60:63], v[130:133], v[146:149], v[60:63]
	v_mfma_f32_16x16x32_bf16 v[56:59], v[138:141], v[146:149], v[56:59]
	v_mfma_f32_16x16x32_bf16 v[52:55], v[130:133], v[154:157], v[52:55]
	v_mfma_f32_16x16x32_bf16 v[44:47], v[138:141], v[154:157], v[44:47]
	v_mfma_f32_16x16x32_bf16 v[36:39], v[130:133], v[162:165], v[36:39]
	v_mfma_f32_16x16x32_bf16 v[28:31], v[138:141], v[162:165], v[28:31]
	v_mfma_f32_16x16x32_bf16 v[20:23], v[130:133], v[194:197], v[20:23]
	v_mfma_f32_16x16x32_bf16 v[12:15], v[138:141], v[194:197], v[12:15]
	v_mfma_f32_16x16x32_bf16 v[60:63], v[134:137], v[150:153], v[60:63]
	v_mfma_f32_16x16x32_bf16 v[56:59], v[142:145], v[150:153], v[56:59]
	v_mfma_f32_16x16x32_bf16 v[52:55], v[134:137], v[158:161], v[52:55]
	v_mfma_f32_16x16x32_bf16 v[44:47], v[142:145], v[158:161], v[44:47]
	v_mfma_f32_16x16x32_bf16 v[36:39], v[134:137], v[190:193], v[36:39]
	v_mfma_f32_16x16x32_bf16 v[28:31], v[142:145], v[190:193], v[28:31]
	v_mfma_f32_16x16x32_bf16 v[20:23], v[134:137], v[198:201], v[20:23]
	v_mfma_f32_16x16x32_bf16 v[12:15], v[142:145], v[198:201], v[12:15]
	s_barrier
	s_add_i32 s44, s78, s57
	v_lshl_add_u64 v[130:131], v[246:247], 0, s[88:89]
	s_mov_b32 m0, s44
	s_nop 0
	global_load_lds_dwordx4 v[130:131], off
	v_lshl_add_u64 v[130:131], v[248:249], 0, s[88:89]
	s_add_i32 m0, s44, 0x2000
	s_nop 0
	global_load_lds_dwordx4 v[130:131], off
	s_waitcnt vmcnt(6)
	s_barrier
	v_mfma_f32_16x16x32_bf16 v[48:51], v[202:205], v[146:149], v[48:51]
	v_mfma_f32_16x16x32_bf16 v[40:43], v[234:237], v[146:149], v[40:43]
	v_mfma_f32_16x16x32_bf16 v[32:35], v[202:205], v[154:157], v[32:35]
	v_mfma_f32_16x16x32_bf16 v[24:27], v[234:237], v[154:157], v[24:27]
	v_mfma_f32_16x16x32_bf16 v[16:19], v[202:205], v[162:165], v[16:19]
	v_mfma_f32_16x16x32_bf16 v[8:11], v[234:237], v[162:165], v[8:11]
	v_mfma_f32_16x16x32_bf16 v[4:7], v[202:205], v[194:197], v[4:7]
	v_mfma_f32_16x16x32_bf16 v[0:3], v[234:237], v[194:197], v[0:3]
	v_mfma_f32_16x16x32_bf16 v[48:51], v[230:233], v[150:153], v[48:51]
	v_mfma_f32_16x16x32_bf16 v[40:43], v[238:241], v[150:153], v[40:43]
	v_mfma_f32_16x16x32_bf16 v[32:35], v[230:233], v[158:161], v[32:35]
	v_mfma_f32_16x16x32_bf16 v[24:27], v[238:241], v[158:161], v[24:27]
	v_mfma_f32_16x16x32_bf16 v[16:19], v[230:233], v[190:193], v[16:19]
	v_mfma_f32_16x16x32_bf16 v[8:11], v[238:241], v[190:193], v[8:11]
	v_mfma_f32_16x16x32_bf16 v[4:7], v[230:233], v[198:201], v[4:7]
	v_mfma_f32_16x16x32_bf16 v[0:3], v[238:241], v[198:201], v[0:3]
	s_add_u32 s36, s36, 0x100
	s_addc_u32 s37, s37, 0
	s_add_u32 s69, s69, 0x100
	s_addc_u32 s70, s70, 0
	s_cmp_ge_u32 s35, s16
	s_mov_b32 s44, s35
	s_barrier
	s_cbranch_scc1 .LBB0_119

; template <class Epi>
; __device__ __forceinline__ void gemm_phase(LAS unsigned char* lds, const Gemm g, const StaticOrder& S, const Epi& E) {
;     ...
;         }
;         E(acc, cur, wr, wc, fr, fq, rsl + (ui & 1) * 256);
;         if (!has_next) break;
.LBB0_119:
	s_cmpk_gt_u32 s79, 0xff
	s_cbranch_scc1 .Lresync_x
	s_barrier

; #define PG8_WAIT_V(n) asm volatile("s_waitcnt vmcnt(" #n ")" ::: "memory")
; #define PG8_BAR __builtin_amdgcn_s_barrier()
; template <class Epi>
; __device__ __forceinline__ void gemm_phase(LAS unsigned char* lds, const Gemm g, const StaticOrder& S, const Epi& E) {
;     ...
;     PG8_WAIT_V(0);
;     if (wr == 0) PG8_BAR;
;     PG8_BAR;
.LBB0_354:
	s_setprio 0
	s_waitcnt vmcnt(0)
	s_branch .LBB0_94
